# diff: persistent MFMA C-operand tuple (beta - m broadcast only re-done when it changes), on top of v9
# baseline (speedup 1.0000x reference)
;     ...
;     float mrun = 0.f, lrun = 0.f;
;     f32x16 O[4]; bf16x8 P[4];
; #pragma unroll
;     for (int e = 0; e < 4; ++e) { O[e] = (f32x16){}; P[e] = (bf16x8){}; }
;     const int qidx = q0w + r32;
;     const int ibq = 128 + 4 * hi - qidx;
;     const int ns = nt >> 1;
;     __syncthreads();
;     if (wid < 4) __builtin_amdgcn_s_setprio(1);
; #pragma unroll 1
;     for (int st = 0; st < ns; ++st) {
; __global__ void __launch_bounds__(512, 2) mk_fwd(Params p) {
;     ...
;             const float lam = tabf[4 * 257];
;             const float* subg = p.in[I_SUBG] + l * 128;
;             bf16_t* DQ = U + S_DQ * SEC_ELEMS; const bf16_t* DK = U + S_DK * SEC_ELEMS; const bf16_t* DV = U + S_DV * SEC_ELEMS;
;     ...
;             for (int rep = 0; rep < 2; ++rep)
;     ...
;             const int rep = 1;
;     ...
;             for (int uu = bid; uu < 2560; uu += G) {
;                 const int rnd = uu >> 8, idx = uu & 255, xcd = idx & 7, slot = idx >> 3; long R0; int S, hd, qb;
;                 if (rnd < 8) { const int pair = rnd * 16 + xcd * 2 + (slot >> 4); R0 = (long)(pair >> 2) * SEQ_P; S = SEQ_P; hd = pair & 3; qb = slot & 15; }
;                 else { const int pair = (rnd - 8) * 4 + (xcd >> 1); R0 = (long)NP_TOK + (long)(pair >> 2) * SEQ_S; S = SEQ_S; hd = pair & 3; qb = (xcd & 1) * 32 + slot; }
;                 diff_unit(lds, DK, DV, DQ, R0, S, hd, qb, lam, 1.f - lam_init, subg, rep == 0);
.LBB0_189:
	v_readlane_b32 s0, v253, 47
	v_readlane_b32 s1, v253, 48
	s_andn2_b64 vcc, exec, s[0:1]
	s_waitcnt lgkmcnt(0)
	v_cndmask_b32_e64 v2, 0, 1, s[0:1]
	v_cmp_ne_u32_e64 s[2:3], 1, v2
	s_barrier
	s_cbranch_vccnz .LBB0_231
	v_readlane_b32 s0, v252, 19
	s_lshl_b32 s84, s82, 7
	v_readlane_b32 s4, v253, 13
	v_mov_b32_e32 v2, s0
	s_lshl_b64 s[0:1], s[84:85], 2
	v_readlane_b32 s8, v253, 17
	v_readlane_b32 s9, v253, 18
	s_add_u32 s0, s8, s0
	v_readlane_b32 s6, v253, 15
	s_addc_u32 s1, s9, s1
	v_readlane_b32 s7, v253, 16
	s_add_u32 s6, s22, 0x19000000
	ds_read_b32 v161, v2
	v_readlane_b32 s12, v253, 21
	s_addc_u32 s7, s23, 0
	v_readlane_b32 s13, v253, 22
	s_add_u32 s12, s22, 0x1e000000
	v_readlane_b32 s14, v253, 23
	s_addc_u32 s13, s23, 0
	v_readlane_b32 s15, v253, 24
	v_readlane_b32 s16, v253, 25
	s_add_u32 s14, s22, 0x23000000
	s_addc_u32 s15, s23, 0
	v_sub_f32_e32 v168, 1.0, v0
	s_mov_b32 s16, s20
	v_readlane_b32 s5, v253, 14
	v_readlane_b32 s10, v253, 19
	v_readlane_b32 s11, v253, 20
	v_readlane_b32 s17, v253, 26
	v_readlane_b32 s18, v253, 27
	v_readlane_b32 s19, v253, 28
	v_mov_b64_e32 v[194:195], 0
	v_mov_b64_e32 v[196:197], 0
	v_mov_b64_e32 v[198:199], 0
	v_mov_b64_e32 v[200:201], 0
	v_mov_b64_e32 v[202:203], 0
	v_mov_b64_e32 v[204:205], 0
	v_mov_b64_e32 v[206:207], 0
	v_mov_b64_e32 v[208:209], 0
	s_branch .LBB0_192

; #define LAS __attribute__((address_space(3)))
; template <bool HAS_QK, bool HAS_PV> ...
;     f32x16 s0, s1;
;     if (HAS_QK) {
;         const float c0 = beta - mrun;
; #pragma unroll
;         for (int r = 0; r < 16; ++r) { s0[r] = c0; s1[r] = c0; }
; #pragma unroll
;         for (int s4 = 0; s4 < 4; ++s4) {
;             const bf16x8 a0 = KFRAG(Kt, kb0, kb1, 0, 0, s4), a1 = KFRAG(Kt, kb0, kb1, 1, 0, s4);
;             s0 = __builtin_amdgcn_mfma_f32_32x32x16_bf16(a0, qf[s4], s0, 0, 0, 0);
;             s1 = __builtin_amdgcn_mfma_f32_32x32x16_bf16(a1, qf[s4], s1, 0, 0, 0);
;         }
;     ...
;         const unsigned bb = (st & 1) * 65536u;
;         if (st + 1 < ns) DIFF_DMA2(st + 1, ((st + 1) & 1) * 65536u);
;         const LAS unsigned char* KA = lds + bb + cmap * 1024; const LAS unsigned char* VA = lds + bb + 16384;
.LBB0_207:
	s_waitcnt lgkmcnt(0)
	v_sub_f32_e32 v14, v0, v15
	v_cmp_neq_f32_e32 vcc, v14, v194
	s_cbranch_vccz .Lcreg_ok_a
	v_mov_b32_e32 v194, v14
	v_mov_b32_e32 v195, v14
	v_mov_b64_e32 v[196:197], v[194:195]
	v_mov_b64_e32 v[198:199], v[194:195]
	v_mov_b64_e32 v[200:201], v[194:195]
	v_mov_b64_e32 v[202:203], v[194:195]
	v_mov_b64_e32 v[204:205], v[194:195]
	v_mov_b64_e32 v[206:207], v[194:195]
	v_mov_b64_e32 v[208:209], v[194:195]
.Lcreg_ok_a:
	s_andn2_b64 vcc, exec, s[4:5]
	s_nop 1
	v_mfma_f32_32x32x16_bf16 v[128:143], v[220:223], v[144:147], v[194:209]
	ds_read_b128 v[220:223], v248 offset:512
	v_mfma_f32_32x32x16_bf16 v[80:95], v[224:227], v[144:147], v[194:209]
	ds_read_b128 v[224:227], v248 offset:8704
	v_mfma_f32_32x32x16_bf16 v[128:143], v[228:231], v[148:151], v[128:143]
	ds_read_b128 v[228:231], v249 offset:512
	v_mfma_f32_32x32x16_bf16 v[80:95], v[232:235], v[148:151], v[80:95]
	ds_read_b128 v[232:235], v249 offset:8704
	s_waitcnt lgkmcnt(3)
	v_mfma_f32_32x32x16_bf16 v[128:143], v[220:223], v[152:155], v[128:143]
	s_waitcnt lgkmcnt(2)
	v_mfma_f32_32x32x16_bf16 v[80:95], v[224:227], v[152:155], v[80:95]
	s_waitcnt lgkmcnt(1)
	v_mfma_f32_32x32x16_bf16 v[128:143], v[228:231], v[156:159], v[128:143]
	s_waitcnt lgkmcnt(0)
	v_mfma_f32_32x32x16_bf16 v[80:95], v[232:235], v[156:159], v[80:95]
	ds_read_b128 v[220:223], v248 offset:32768
	ds_read_b128 v[224:227], v249 offset:32768
	ds_read_b128 v[228:231], v248 offset:33280
	ds_read_b128 v[232:235], v249 offset:33280
	s_cmp_ge_u32 s35, s17
	s_cbranch_scc1 .Ldiff_nodma
	s_and_b32 s4, s34, 0x10000
	s_add_i32 s4, s24, s4
	v_readlane_b32 s10, v247, 0
	v_readlane_b32 s11, v247, 1
	s_add_i32 s56, s29, 0x80
	s_lshl_b32 s56, s56, 10
	s_add_u32 s10, s10, s56
	s_addc_u32 s11, s11, 0
	s_add_u32 s56, s10, s72
	s_addc_u32 s57, s11, s73
	s_mov_b32 m0, s4
	s_nop 0
	global_load_lds_dwordx4 v250, s[56:57]
	s_add_i32 m0, s4, 0x2000
	s_nop 0
	global_load_lds_dwordx4 v251, s[56:57]
	s_add_u32 s56, s10, s74
	s_addc_u32 s57, s11, s75
	s_add_i32 m0, s4, 0x4000
	s_nop 0
	global_load_lds_dwordx4 v250, s[56:57]
	s_add_i32 m0, s4, 0x6000
	s_nop 0
	global_load_lds_dwordx4 v251, s[56:57]
	s_add_u32 s56, s10, s68
	s_addc_u32 s57, s11, s69
	s_add_i32 m0, s4, 0x8000
	s_nop 0
	global_load_lds_dwordx4 v250, s[56:57]
	s_add_i32 m0, s4, 0xa000
	s_nop 0
	global_load_lds_dwordx4 v251, s[56:57]
	s_add_u32 s56, s10, s96
	s_addc_u32 s57, s11, s97
	s_add_i32 m0, s4, 0xc000
	s_nop 0
	global_load_lds_dwordx4 v250, s[56:57]
	s_add_i32 m0, s4, 0xe000
	s_nop 0
	global_load_lds_dwordx4 v251, s[56:57]
	s_branch .Ldiff_dma_done

; template <bool HAS_QK, bool HAS_PV> ...
;     f32x16 s0, s1;
;     if (HAS_QK) {
;         const float c0 = beta - mrun;
; #pragma unroll
;         for (int r = 0; r < 16; ++r) { s0[r] = c0; s1[r] = c0; }
; #pragma unroll
;         for (int s4 = 0; s4 < 4; ++s4) {
;             const bf16x8 a0 = KFRAG(Kt, kb0, kb1, 0, 0, s4), a1 = KFRAG(Kt, kb0, kb1, 1, 0, s4);
;             s0 = __builtin_amdgcn_mfma_f32_32x32x16_bf16(a0, qf[s4], s0, 0, 0, 0);
;             s1 = __builtin_amdgcn_mfma_f32_32x32x16_bf16(a1, qf[s4], s1, 0, 0, 0);
;         }
;     }
;     if (HAS_PV) {
; #pragma unroll
;         for (int ks = 0; ks < 2; ++ks)
; #pragma unroll
;             for (int c4 = 0; c4 < 4; ++c4) { const bf16x8 vf = vfrag(Vp, vb0, vb1, ks, c4); O[c4] = __builtin_amdgcn_mfma_f32_32x32x16_bf16(vf, P[ks], O[c4], 0, 0, 0); }
;     }
;     float f = 1.f; bool need = false;
;     if (HAS_QK) {
;         if (NEAR) {
; #pragma unroll
;             for (int r = 0; r < 16; ++r) { int i0 = ib0 + (r & 3) + 8 * (r >> 2), i1 = i0 + 32; i0 = min(max(i0, 0), 256); i1 = min(max(i1, 0), 256); s0[r] += tab[i0]; s1[r] += tab[i1]; }
;         }
;         const float rm = rowmax32(s0, s1);
;         need = first || __any(rm > 8.f);
;         if (need) { const float dl = first ? rm : fmaxf(rm, 0.f); mrun += dl; f = first ? 1.f : __builtin_amdgcn_exp2f(-dl);
; #pragma unroll
;             for (int r = 0; r < 16; ++r) { s0[r] -= dl; s1[r] -= dl; } }
;     }
;     if (HAS_PV) {
; #pragma unroll
;         for (int ks = 2; ks < 4; ++ks)
; #pragma unroll
;             for (int c4 = 0; c4 < 4; ++c4) { const bf16x8 vf = vfrag(Vp, vb0, vb1, ks, c4); O[c4] = __builtin_amdgcn_mfma_f32_32x32x16_bf16(vf, P[ks], O[c4], 0, 0, 0); }
;     }
.LBB0_220:
	s_waitcnt lgkmcnt(0)
	v_sub_f32_e32 v14, v4, v15
	v_cmp_neq_f32_e32 vcc, v14, v194
	s_cbranch_vccz .Lcreg_ok_b
	v_mov_b32_e32 v194, v14
	v_mov_b32_e32 v195, v14
	v_mov_b64_e32 v[196:197], v[194:195]
	v_mov_b64_e32 v[198:199], v[194:195]
	v_mov_b64_e32 v[200:201], v[194:195]
	v_mov_b64_e32 v[202:203], v[194:195]
	v_mov_b64_e32 v[204:205], v[194:195]
	v_mov_b64_e32 v[206:207], v[194:195]
	v_mov_b64_e32 v[208:209], v[194:195]
.Lcreg_ok_b:
	v_exp_f32_e32 v180, v129
	v_exp_f32_e32 v179, v128
	v_mfma_f32_32x32x16_bf16 v[112:127], v[220:223], v[144:147], v[194:209]
	ds_read_b64_tr_b16 v[220:221], v237 offset:16384
	ds_read_b64_tr_b16 v[222:223], v236 offset:18432
	v_exp_f32_e32 v130, v130
	v_exp_f32_e32 v131, v131
	v_exp_f32_e32 v132, v132
	v_exp_f32_e32 v133, v133
	v_mfma_f32_32x32x16_bf16 v[112:127], v[224:227], v[148:151], v[112:127]
	ds_read_b64_tr_b16 v[224:225], v237 offset:16896
	ds_read_b64_tr_b16 v[226:227], v236 offset:18944
	v_exp_f32_e32 v134, v134
	v_exp_f32_e32 v135, v135
	v_exp_f32_e32 v136, v136
	v_exp_f32_e32 v137, v137
	v_exp_f32_e32 v138, v138
	v_exp_f32_e32 v139, v139
	v_mfma_f32_32x32x16_bf16 v[112:127], v[228:231], v[152:155], v[112:127]
	ds_read_b64_tr_b16 v[228:229], v237 offset:17408
	ds_read_b64_tr_b16 v[230:231], v236 offset:19456
	v_exp_f32_e32 v140, v140
	v_exp_f32_e32 v141, v141
	v_exp_f32_e32 v142, v142
	v_exp_f32_e32 v143, v143
	s_andn2_b64 vcc, exec, s[4:5]
	v_mfma_f32_32x32x16_bf16 v[112:127], v[232:235], v[156:159], v[112:127]
	ds_read_b64_tr_b16 v[232:233], v237 offset:17920
	ds_read_b64_tr_b16 v[234:235], v236 offset:19968
	v_cvt_pk_bf16_f32 v8, v179, v180
	v_cvt_pk_bf16_f32 v9, v130, v131
	v_cvt_pk_bf16_f32 v10, v132, v133
	v_cvt_pk_bf16_f32 v11, v134, v135
	s_waitcnt lgkmcnt(6)
	s_nop 0
	v_mfma_f32_32x32x16_bf16 v[64:79], v[220:223], v[8:11], v[64:79]
	ds_read_b64_tr_b16 v[220:221], v237 offset:20480
	ds_read_b64_tr_b16 v[222:223], v236 offset:22528
	v_exp_f32_e32 v80, v80
	v_exp_f32_e32 v81, v81
	s_waitcnt lgkmcnt(6)
	v_mfma_f32_32x32x16_bf16 v[48:63], v[224:227], v[8:11], v[48:63]
	ds_read_b64_tr_b16 v[224:225], v237 offset:20992
	ds_read_b64_tr_b16 v[226:227], v236 offset:23040
	v_exp_f32_e32 v82, v82
	v_exp_f32_e32 v83, v83
	s_waitcnt lgkmcnt(6)
	v_mfma_f32_32x32x16_bf16 v[32:47], v[228:231], v[8:11], v[32:47]
	ds_read_b64_tr_b16 v[228:229], v237 offset:21504
	ds_read_b64_tr_b16 v[230:231], v236 offset:23552
	v_exp_f32_e32 v84, v84
	v_exp_f32_e32 v85, v85
	s_waitcnt lgkmcnt(6)
	v_mfma_f32_32x32x16_bf16 v[16:31], v[232:235], v[8:11], v[16:31]
	ds_read_b64_tr_b16 v[232:233], v237 offset:22016
	ds_read_b64_tr_b16 v[234:235], v236 offset:24064
	v_exp_f32_e32 v86, v86
	v_exp_f32_e32 v87, v87
	v_cvt_pk_bf16_f32 v8, v136, v137
	v_cvt_pk_bf16_f32 v9, v138, v139
	v_cvt_pk_bf16_f32 v10, v140, v141
	v_cvt_pk_bf16_f32 v11, v142, v143
	s_waitcnt lgkmcnt(6)
	s_nop 0
	v_mfma_f32_32x32x16_bf16 v[64:79], v[220:223], v[8:11], v[64:79]
	ds_read_b128 v[220:223], v248 offset:40960
	v_exp_f32_e32 v88, v88
	v_exp_f32_e32 v89, v89
	s_waitcnt lgkmcnt(5)
	v_mfma_f32_32x32x16_bf16 v[48:63], v[224:227], v[8:11], v[48:63]
	ds_read_b128 v[224:227], v249 offset:40960
	v_exp_f32_e32 v90, v90
	v_exp_f32_e32 v91, v91
	s_waitcnt lgkmcnt(4)
	v_mfma_f32_32x32x16_bf16 v[32:47], v[228:231], v[8:11], v[32:47]
	ds_read_b128 v[228:231], v248 offset:41472
	v_exp_f32_e32 v92, v92
	v_exp_f32_e32 v93, v93
	s_waitcnt lgkmcnt(3)
	v_mfma_f32_32x32x16_bf16 v[16:31], v[232:235], v[8:11], v[16:31]
	ds_read_b128 v[232:235], v249 offset:41472
	v_exp_f32_e32 v94, v94
	v_exp_f32_e32 v95, v95
	s_waitcnt lgkmcnt(3)
	v_mfma_f32_32x32x16_bf16 v[96:111], v[220:223], v[144:147], v[194:209]
	ds_read_b64_tr_b16 v[220:221], v237 offset:24576
	ds_read_b64_tr_b16 v[222:223], v236 offset:26624
	s_waitcnt lgkmcnt(4)
	v_mfma_f32_32x32x16_bf16 v[96:111], v[224:227], v[148:151], v[96:111]
	ds_read_b64_tr_b16 v[224:225], v237 offset:25088
	ds_read_b64_tr_b16 v[226:227], v236 offset:27136
	s_waitcnt lgkmcnt(5)
	v_mfma_f32_32x32x16_bf16 v[96:111], v[228:231], v[152:155], v[96:111]
	ds_read_b64_tr_b16 v[228:229], v237 offset:25600
	ds_read_b64_tr_b16 v[230:231], v236 offset:27648
	s_waitcnt lgkmcnt(6)
	v_mfma_f32_32x32x16_bf16 v[96:111], v[232:235], v[156:159], v[96:111]
	ds_read_b64_tr_b16 v[232:233], v237 offset:26112
	ds_read_b64_tr_b16 v[234:235], v236 offset:28160
	s_cbranch_vccnz .LBB0_222
; template <bool HAS_QK, bool HAS_PV> ...
;     ...
;         if (NEAR) {
; #pragma unroll
;             for (int r = 0; r < 16; ++r) { int i0 = ib0 + (r & 3) + 8 * (r >> 2), i1 = i0 + 32; i0 = min(max(i0, 0), 256); i1 = min(max(i1, 0), 256); s0[r] += tab[i0]; s1[r] += tab[i1]; }
;         }
	v_add_u32_e32 v14, s29, v176
	v_add_u32_e32 v2, 0xc0, v14
	v_med3_i32 v3, v2, 0, v246
	v_max_i32_e32 v2, 0xffffffe0, v2
	v_add_u32_e32 v2, 32, v2
	v_min_u32_e32 v2, 0x100, v2
	v_lshl_add_u32 v4, v2, 2, s25
	v_add_u32_e32 v2, 0xc1, v14
	v_med3_i32 v5, v2, 0, v246
	v_max_i32_e32 v2, 0xffffffe0, v2
	v_add_u32_e32 v2, 32, v2
	v_min_u32_e32 v2, 0x100, v2
	v_lshl_add_u32 v6, v2, 2, s25
	v_add_u32_e32 v2, 0xc2, v14
	v_med3_i32 v7, v2, 0, v246
	v_max_i32_e32 v2, 0xffffffe0, v2
	v_add_u32_e32 v2, 32, v2
	v_min_u32_e32 v2, 0x100, v2
	v_lshl_add_u32 v8, v2, 2, s25
	v_add_u32_e32 v2, 0xc3, v14
	v_med3_i32 v9, v2, 0, v246
	v_max_i32_e32 v2, 0xffffffe0, v2
	v_add_u32_e32 v2, 32, v2
	v_min_u32_e32 v2, 0x100, v2
	v_lshl_add_u32 v3, v3, 2, s25
	v_lshl_add_u32 v5, v5, 2, s25
	v_lshl_add_u32 v7, v7, 2, s25
	v_lshl_add_u32 v9, v9, 2, s25
	v_lshl_add_u32 v10, v2, 2, s25
	ds_read_b32 v2, v3
	ds_read_b32 v4, v4
	ds_read_b32 v3, v5
	ds_read_b32 v5, v6
	ds_read_b32 v6, v7
	ds_read_b32 v8, v8
	ds_read_b32 v7, v9
	ds_read_b32 v9, v10
	v_add_u32_e32 v10, 0xc8, v14
	v_med3_i32 v11, v10, 0, v246
	v_max_i32_e32 v10, 0xffffffe0, v10
	v_add_u32_e32 v10, 32, v10
	v_min_u32_e32 v10, 0x100, v10
	v_lshl_add_u32 v12, v10, 2, s25
	v_add_u32_e32 v10, 0xc9, v14
	v_med3_i32 v13, v10, 0, v246
	v_max_i32_e32 v10, 0xffffffe0, v10
	v_add_u32_e32 v10, 32, v10
	v_min_u32_e32 v10, 0x100, v10
	v_lshl_add_u32 v181, v10, 2, s25
	v_add_u32_e32 v10, 0xca, v14
	v_med3_i32 v182, v10, 0, v246
	v_max_i32_e32 v10, 0xffffffe0, v10
	v_add_u32_e32 v187, 0xd1, v14
	v_add_u32_e32 v10, 32, v10
	v_med3_i32 v188, v187, 0, v246
	v_max_i32_e32 v187, 0xffffffe0, v187
	v_min_u32_e32 v10, 0x100, v10
	v_add_u32_e32 v187, 32, v187
	v_lshl_add_u32 v183, v10, 2, s25
	v_add_u32_e32 v10, 0xcb, v14
	v_min_u32_e32 v187, 0x100, v187
	v_med3_i32 v184, v10, 0, v246
	v_max_i32_e32 v10, 0xffffffe0, v10
	v_lshl_add_u32 v190, v187, 2, s25
	v_add_u32_e32 v187, 0xd2, v14
	v_add_u32_e32 v10, 32, v10
	v_lshl_add_u32 v189, v188, 2, s25
	v_med3_i32 v188, v187, 0, v246
	v_max_i32_e32 v187, 0xffffffe0, v187
	v_lshl_add_u32 v11, v11, 2, s25
	v_lshl_add_u32 v13, v13, 2, s25
	v_lshl_add_u32 v182, v182, 2, s25
	v_min_u32_e32 v10, 0x100, v10
	v_lshl_add_u32 v185, v184, 2, s25
	v_add_u32_e32 v187, 32, v187
	v_lshl_add_u32 v186, v10, 2, s25
	ds_read_b32 v10, v11
	ds_read_b32 v12, v12
	ds_read_b32 v11, v13
	ds_read_b32 v13, v181
	ds_read_b32 v182, v182
	ds_read_b32 v184, v183
	ds_read_b32 v183, v185
	ds_read_b32 v185, v186
	v_add_u32_e32 v181, 0xd0, v14
	v_min_u32_e32 v187, 0x100, v187
	v_med3_i32 v186, v181, 0, v246
	v_max_i32_e32 v181, 0xffffffe0, v181
	v_lshl_add_u32 v192, v187, 2, s25
	v_add_u32_e32 v187, 0xd3, v14
	v_add_u32_e32 v211, 0xd9, v14
	v_add_u32_e32 v181, 32, v181
	v_lshl_add_u32 v191, v188, 2, s25
	v_med3_i32 v188, v187, 0, v246
	v_max_i32_e32 v187, 0xffffffe0, v187
	v_med3_i32 v212, v211, 0, v246
	v_min_u32_e32 v181, 0x100, v181
	v_add_u32_e32 v187, 32, v187
	v_max_i32_e32 v211, 0xffffffe0, v211
	v_lshl_add_u32 v213, v212, 2, s25
	v_add_u32_e32 v212, s29, v177
	v_lshl_add_u32 v186, v186, 2, s25
	v_lshl_add_u32 v181, v181, 2, s25
	v_min_u32_e32 v187, 0x100, v187
	v_lshl_add_u32 v193, v188, 2, s25
	v_add_u32_e32 v211, 32, v211
	v_add_u32_e32 v212, 0xdb, v212
	v_lshl_add_u32 v210, v187, 2, s25
	ds_read_b32 v186, v186
	ds_read_b32 v188, v181
	ds_read_b32 v187, v189
	ds_read_b32 v189, v190
	ds_read_b32 v190, v191
	ds_read_b32 v192, v192
	ds_read_b32 v191, v193
	ds_read_b32 v193, v210
	v_add_u32_e32 v181, 0xd8, v14
	v_min_u32_e32 v211, 0x100, v211
	v_add_u32_e32 v14, 0xda, v14
	v_med3_i32 v214, v212, 0, v246
	v_max_i32_e32 v212, 0xffffffe0, v212
	v_med3_i32 v210, v181, 0, v246
	v_max_i32_e32 v181, 0xffffffe0, v181
	v_lshl_add_u32 v218, v211, 2, s25
	v_med3_i32 v211, v14, 0, v246
	v_max_i32_e32 v14, 0xffffffe0, v14
	v_add_u32_e32 v212, 32, v212
	v_add_u32_e32 v181, 32, v181
	v_add_u32_e32 v14, 32, v14
	v_min_u32_e32 v212, 0x100, v212
	v_min_u32_e32 v181, 0x100, v181
	v_lshl_add_u32 v210, v210, 2, s25
	v_min_u32_e32 v14, 0x100, v14
	v_lshl_add_u32 v211, v211, 2, s25
	v_lshl_add_u32 v215, v214, 2, s25
	v_lshl_add_u32 v216, v212, 2, s25
	v_lshl_add_u32 v181, v181, 2, s25
	v_lshl_add_u32 v14, v14, 2, s25
	ds_read_b32 v210, v210
	ds_read_b32 v212, v181
	ds_read_b32 v214, v211
	ds_read_b32 v215, v215
	ds_read_b32 v211, v213
	ds_read_b32 v217, v216
	ds_read_b32 v216, v14
	ds_read_b32 v213, v218
	s_waitcnt lgkmcnt(0)
	v_pk_add_f32 v[126:127], v[126:127], v[214:215]
	v_pk_add_f32 v[124:125], v[124:125], v[210:211]
	v_pk_add_f32 v[122:123], v[122:123], v[190:191]
	v_pk_add_f32 v[120:121], v[120:121], v[186:187]
	v_pk_add_f32 v[118:119], v[118:119], v[182:183]
	v_pk_add_f32 v[116:117], v[116:117], v[10:11]
	v_pk_add_f32 v[114:115], v[114:115], v[6:7]
	v_pk_add_f32 v[112:113], v[112:113], v[2:3]
	v_pk_add_f32 v[110:111], v[110:111], v[216:217]
	v_pk_add_f32 v[108:109], v[108:109], v[212:213]
	v_pk_add_f32 v[106:107], v[106:107], v[192:193]
	v_pk_add_f32 v[104:105], v[104:105], v[188:189]
	v_pk_add_f32 v[102:103], v[102:103], v[184:185]
	v_pk_add_f32 v[100:101], v[100:101], v[12:13]
	v_pk_add_f32 v[98:99], v[98:99], v[8:9]
	v_pk_add_f32 v[96:97], v[96:97], v[4:5]

; __global__ void __launch_bounds__(512, 2) mk_fwd(Params p) {
;     ...
;             __syncthreads();
;             for (int i = tid; i < 8 * 465; i += 512) tabf[i] = p.in[I_RPB][l * 3720 + i] * LOG2E;
;             __syncthreads();
.LBB0_231:
	v_mov_b64_e32 v[194:195], 0x1400
	v_mov_b64_e32 v[196:197], 0x13ff
	v_mov_b64_e32 v[198:199], 0xf00
	v_mov_b64_e32 v[200:201], 0xeff
	v_mov_b64_e32 v[202:203], 0x500
	v_mov_b64_e32 v[204:205], 0x4ff
	v_mov_b64_e32 v[206:207], 0x1b80
	v_mov_b64_e32 v[208:209], 0x1b7f
	s_movk_i32 s0, 0xe88
	v_cmp_gt_i32_e32 vcc, s0, v160
	s_barrier
	s_and_saveexec_b64 s[0:1], vcc
	s_cbranch_execz .LBB0_244
	v_max_i32_e32 v0, 0xc88, v160
	v_sub_u32_e32 v0, v0, v160
	v_add_u32_e32 v0, 0x1ff, v0
	s_movk_i32 s4, 0x1ff
	v_cmp_lt_u32_e32 vcc, s4, v0
	s_mov_b64 s[6:7], -1
	s_and_saveexec_b64 s[4:5], vcc
	s_cbranch_execz .LBB0_241
	v_lshrrev_b32_e32 v0, 9, v0
	v_add_u32_e32 v2, -1, v0
	v_add_u32_e32 v161, 0x200, v160
	v_lshrrev_b32_e32 v3, 1, v2
	s_mul_i32 s10, s82, 0xe88
	v_add_u32_e32 v4, 1, v3
	v_cmp_lt_u32_e32 vcc, 5, v2
	v_mov_b32_e32 v7, 0
	v_mov_b64_e32 v[2:3], v[160:161]
	s_and_saveexec_b64 s[6:7], vcc
	s_cbranch_execz .LBB0_237
	s_mov_b64 s[18:19], s[40:41]
	s_add_i32 s11, s10, 0x400
	s_add_i32 s13, s10, 0x800
	s_add_i32 s15, s10, 0xc00
	v_readlane_b32 s8, v252, 18
	v_readlane_b32 s40, v253, 29
	v_and_b32_e32 v5, -4, v4
	s_mov_b32 s12, s11
	s_mov_b32 s14, s13
	s_mov_b32 s16, s15
	v_lshl_add_u32 v6, v160, 2, s8
	s_mov_b32 s17, 0
	s_mov_b64 s[8:9], 0
	v_mov_b64_e32 v[2:3], v[160:161]
	v_readlane_b32 s48, v253, 37
	v_readlane_b32 s49, v253, 38
	v_readlane_b32 s41, v253, 30
	v_readlane_b32 s42, v253, 31
	v_readlane_b32 s43, v253, 32
	v_readlane_b32 s44, v253, 33
	v_readlane_b32 s45, v253, 34
	v_readlane_b32 s46, v253, 35
	v_readlane_b32 s47, v253, 36
	v_readlane_b32 s50, v253, 39
	v_readlane_b32 s51, v253, 40
	v_readlane_b32 s52, v253, 41
	v_readlane_b32 s53, v253, 42
	v_readlane_b32 s54, v253, 43
	v_readlane_b32 s55, v253, 44
